# final phase output stores with default policy instead of nt (policy sweep, on top of v70)
# speedup vs baseline: 1.0391x; 1.0391x over previous
; __device__ __forceinline__ void final_phase(CArgs* a, int gw, int NGW, int lane) {
;     ...
;         for (int rr = 0; rr < 2; ++rr) { const int m = mb + rr * NGW; if (m < M) { sp[rr] = ssp[(size_t)m * 16 + (lane & 15)];
; #pragma unroll
;             for (int j = 0; j < 2; ++j) raw[rr][j] = *((const v4u*)(XB + (size_t)m * D) + lane + 64 * j); } }
; #pragma unroll
;         for (int rr = 0; rr < 2; ++rr) { const int m = mb + rr * NGW; if (m < M) { float s = sp[rr];
;             s += __shfl_xor(s, 1); s += __shfl_xor(s, 2); s += __shfl_xor(s, 4); s += __shfl_xor(s, 8);
;             const float r = __builtin_amdgcn_rsqf(s * (1.f / 1024.f) + EPS);
; #pragma unroll
;             for (int j = 0; j < 2; ++j) { const v4u w = raw[rr][j]; const int col = 8 * (lane + 64 * j);
;                 const f32x4 g0 = *(const f32x4*)(g + col), g1 = *(const f32x4*)(g + col + 4);
;                 const f32x4 v0 = (f32x4){__builtin_bit_cast(float, w.x << 16), __builtin_bit_cast(float, w.x & 0xffff0000u), __builtin_bit_cast(float, w.y << 16), __builtin_bit_cast(float, w.y & 0xffff0000u)};
;                 const f32x4 v1 = (f32x4){__builtin_bit_cast(float, w.z << 16), __builtin_bit_cast(float, w.z & 0xffff0000u), __builtin_bit_cast(float, w.w << 16), __builtin_bit_cast(float, w.w & 0xffff0000u)};
;                 __builtin_nontemporal_store(v0 * r * g0, (f32x4*)(X + (size_t)m * D + col)); __builtin_nontemporal_store(v1 * r * g1, (f32x4*)(X + (size_t)m * D + col + 4)); } } } }
.LBB0_1137:
	global_load_dwordx4 v[8:11], v[22:23], off
	global_load_dwordx4 v[12:15], v[22:23], off offset:16
	ds_bpermute_b32 v30, v18, v19
	s_ashr_i32 s1, s0, 31
	v_lshlrev_b32_e32 v32, 16, v5
	v_and_b32_e32 v35, 0xffff0000, v6
	v_lshlrev_b32_e32 v36, 16, v7
	s_waitcnt lgkmcnt(0)
	v_add_f32_e32 v30, v19, v30
	ds_bpermute_b32 v31, v26, v30
	s_lshl_b64 s[2:3], s[0:1], 12
	v_lshl_add_u64 v[40:41], v[24:25], 0, s[2:3]
	s_waitcnt lgkmcnt(0)
	v_add_f32_e32 v33, v30, v31
	ds_bpermute_b32 v34, v27, v33
	v_lshlrev_b32_e32 v30, 16, v4
	v_and_b32_e32 v31, 0xffff0000, v4
	s_waitcnt lgkmcnt(0)
	v_add_f32_e32 v37, v33, v34
	ds_bpermute_b32 v38, v28, v37
	v_and_b32_e32 v33, 0xffff0000, v5
	v_lshlrev_b32_e32 v34, 16, v6
	s_waitcnt lgkmcnt(0)
	v_add_f32_e32 v37, v37, v38
	v_fmamk_f32 v37, v37, 0x3a800000, v29
	v_rsq_f32_e32 v38, v37
	v_and_b32_e32 v37, 0xffff0000, v7
	v_pk_mul_f32 v[30:31], v[38:39], v[30:31] op_sel_hi:[0,1]
	v_pk_mul_f32 v[32:33], v[38:39], v[32:33] op_sel_hi:[0,1]
	v_pk_mul_f32 v[34:35], v[38:39], v[34:35] op_sel_hi:[0,1]
	v_pk_mul_f32 v[36:37], v[38:39], v[36:37] op_sel_hi:[0,1]
	s_waitcnt vmcnt(1)
	v_pk_mul_f32 v[10:11], v[10:11], v[32:33]
	v_pk_mul_f32 v[8:9], v[8:9], v[30:31]
	s_waitcnt vmcnt(0)
	v_pk_mul_f32 v[14:15], v[14:15], v[36:37]
	v_pk_mul_f32 v[12:13], v[12:13], v[34:35]
	global_store_dwordx4 v[40:41], v[8:11], off
	global_store_dwordx4 v[40:41], v[12:15], off offset:16
	global_load_dwordx4 v[8:11], v[22:23], off offset:2048
	s_nop 0
	global_load_dwordx4 v[12:15], v[22:23], off offset:2064
	v_lshlrev_b32_e32 v30, 16, v0
	v_and_b32_e32 v31, 0xffff0000, v0
	v_lshlrev_b32_e32 v32, 16, v1
	v_and_b32_e32 v33, 0xffff0000, v1
	v_lshlrev_b32_e32 v34, 16, v2
	v_and_b32_e32 v35, 0xffff0000, v2
	v_lshlrev_b32_e32 v36, 16, v3
	v_and_b32_e32 v37, 0xffff0000, v3
	v_pk_mul_f32 v[32:33], v[38:39], v[32:33] op_sel_hi:[0,1]
	v_pk_mul_f32 v[30:31], v[38:39], v[30:31] op_sel_hi:[0,1]
	v_pk_mul_f32 v[36:37], v[38:39], v[36:37] op_sel_hi:[0,1]
	v_pk_mul_f32 v[34:35], v[38:39], v[34:35] op_sel_hi:[0,1]
	s_waitcnt vmcnt(1)
	v_pk_mul_f32 v[8:9], v[8:9], v[30:31]
	v_pk_mul_f32 v[10:11], v[10:11], v[32:33]
	s_waitcnt vmcnt(0)
	v_pk_mul_f32 v[12:13], v[12:13], v[34:35]
	v_pk_mul_f32 v[14:15], v[14:15], v[36:37]
	global_store_dwordx4 v[40:41], v[8:11], off offset:2048
	global_store_dwordx4 v[40:41], v[12:15], off offset:2064

; __device__ __forceinline__ void final_phase(CArgs* a, int gw, int NGW, int lane) {
;     ...
;         for (int rr = 0; rr < 2; ++rr) { const int m = mb + rr * NGW; if (m < M) { sp[rr] = ssp[(size_t)m * 16 + (lane & 15)];
; #pragma unroll
;             for (int j = 0; j < 2; ++j) raw[rr][j] = *((const v4u*)(XB + (size_t)m * D) + lane + 64 * j); } }
; #pragma unroll
;         for (int rr = 0; rr < 2; ++rr) { const int m = mb + rr * NGW; if (m < M) { float s = sp[rr];
;             s += __shfl_xor(s, 1); s += __shfl_xor(s, 2); s += __shfl_xor(s, 4); s += __shfl_xor(s, 8);
;             const float r = __builtin_amdgcn_rsqf(s * (1.f / 1024.f) + EPS);
; #pragma unroll
;             for (int j = 0; j < 2; ++j) { const v4u w = raw[rr][j]; const int col = 8 * (lane + 64 * j);
;                 const f32x4 g0 = *(const f32x4*)(g + col), g1 = *(const f32x4*)(g + col + 4);
;                 const f32x4 v0 = (f32x4){__builtin_bit_cast(float, w.x << 16), __builtin_bit_cast(float, w.x & 0xffff0000u), __builtin_bit_cast(float, w.y << 16), __builtin_bit_cast(float, w.y & 0xffff0000u)};
;                 const f32x4 v1 = (f32x4){__builtin_bit_cast(float, w.z << 16), __builtin_bit_cast(float, w.z & 0xffff0000u), __builtin_bit_cast(float, w.w << 16), __builtin_bit_cast(float, w.w & 0xffff0000u)};
;                 __builtin_nontemporal_store(v0 * r * g0, (f32x4*)(X + (size_t)m * D + col)); __builtin_nontemporal_store(v1 * r * g1, (f32x4*)(X + (size_t)m * D + col + 4)); } } } }
.LBB0_1141:
	s_nop 0
	global_load_dwordx4 v[32:35], v[22:23], off
	global_load_dwordx4 v[36:39], v[22:23], off offset:16
	s_waitcnt vmcnt(4)
	ds_bpermute_b32 v31, v18, v30
	s_lshl_b64 s[4:5], s[8:9], 12
	v_lshl_add_u64 v[44:45], v[24:25], 0, s[4:5]
	s_andn2_b64 vcc, exec, s[2:3]
	s_waitcnt lgkmcnt(0)
	v_add_f32_e32 v30, v30, v31
	ds_bpermute_b32 v31, v26, v30
	s_waitcnt lgkmcnt(0)
	v_add_f32_e32 v40, v30, v31
	ds_bpermute_b32 v41, v27, v40
	s_waitcnt vmcnt(3)
	v_lshlrev_b32_e32 v30, 16, v12
	v_and_b32_e32 v31, 0xffff0000, v12
	v_lshlrev_b32_e32 v12, 16, v13
	v_and_b32_e32 v13, 0xffff0000, v13
	s_waitcnt lgkmcnt(0)
	v_add_f32_e32 v42, v40, v41
	ds_bpermute_b32 v43, v28, v42
	v_lshlrev_b32_e32 v40, 16, v14
	v_and_b32_e32 v41, 0xffff0000, v14
	s_waitcnt lgkmcnt(0)
	v_add_f32_e32 v14, v42, v43
	v_fmamk_f32 v14, v14, 0x3a800000, v29
	v_rsq_f32_e32 v42, v14
	v_lshlrev_b32_e32 v14, 16, v15
	v_and_b32_e32 v15, 0xffff0000, v15
	v_pk_mul_f32 v[30:31], v[42:43], v[30:31] op_sel_hi:[0,1]
	v_pk_mul_f32 v[12:13], v[42:43], v[12:13] op_sel_hi:[0,1]
	v_pk_mul_f32 v[40:41], v[42:43], v[40:41] op_sel_hi:[0,1]
	v_pk_mul_f32 v[46:47], v[42:43], v[14:15] op_sel_hi:[0,1]
	s_waitcnt vmcnt(1)
	v_pk_mul_f32 v[14:15], v[34:35], v[12:13]
	v_pk_mul_f32 v[12:13], v[32:33], v[30:31]
	s_waitcnt vmcnt(0)
	v_pk_mul_f32 v[32:33], v[38:39], v[46:47]
	v_pk_mul_f32 v[30:31], v[36:37], v[40:41]
	global_store_dwordx4 v[44:45], v[12:15], off
	global_store_dwordx4 v[44:45], v[30:33], off offset:16
	global_load_dwordx4 v[12:15], v[22:23], off offset:2048
	s_nop 0
	global_load_dwordx4 v[30:33], v[22:23], off offset:2064
	v_lshlrev_b32_e32 v34, 16, v8
	v_and_b32_e32 v35, 0xffff0000, v8
	v_lshlrev_b32_e32 v8, 16, v9
	v_and_b32_e32 v9, 0xffff0000, v9
	v_lshlrev_b32_e32 v36, 16, v10
	v_and_b32_e32 v37, 0xffff0000, v10
	v_lshlrev_b32_e32 v10, 16, v11
	v_and_b32_e32 v11, 0xffff0000, v11
	v_pk_mul_f32 v[38:39], v[42:43], v[8:9] op_sel_hi:[0,1]
	v_pk_mul_f32 v[8:9], v[42:43], v[34:35] op_sel_hi:[0,1]
	v_pk_mul_f32 v[34:35], v[42:43], v[10:11] op_sel_hi:[0,1]
	v_pk_mul_f32 v[36:37], v[42:43], v[36:37] op_sel_hi:[0,1]
	s_waitcnt vmcnt(1)
	v_pk_mul_f32 v[8:9], v[12:13], v[8:9]
	v_pk_mul_f32 v[10:11], v[14:15], v[38:39]
	s_waitcnt vmcnt(0)
	v_pk_mul_f32 v[12:13], v[30:31], v[36:37]
	v_pk_mul_f32 v[14:15], v[32:33], v[34:35]
	global_store_dwordx4 v[44:45], v[8:11], off offset:2048
	global_store_dwordx4 v[44:45], v[12:15], off offset:2064
	s_cbranch_vccnz .LBB0_1143
	s_cbranch_execnz .LBB0_1138
	s_branch .LBB0_1137
